# MoBA fast paths: packed f32 adds (row sums) split into scalar adds beside the MFMAs
# speedup vs baseline: 1.0006x; 1.0002x over previous
.Lm_fastA:
	ds_read_b128 v[196:199], v179
	ds_read_b128 v[200:203], v179 offset:512
	ds_read_b128 v[204:207], v179 offset:2080
	ds_read_b128 v[208:211], v179 offset:2592
	ds_read_b128 v[212:215], v179 offset:4160
	ds_read_b128 v[216:219], v179 offset:4672
	ds_read_b128 v[188:191], v179 offset:6240
	ds_read_b128 v[224:227], v179 offset:6752
	v_max_f32_e32 v238, v32, v32
	v_max_f32_e32 v239, v48, v48
	v_max3_f32 v238, v238, v33, v34
	v_max3_f32 v239, v239, v49, v50
	v_max3_f32 v238, v238, v35, v36
	s_waitcnt lgkmcnt(7)
	v_mfma_f32_32x32x16_bf16 v[64:79], v[196:199], v[128:131], 0
	v_max3_f32 v239, v239, v51, v52
	v_max3_f32 v238, v238, v37, v38
	v_max3_f32 v239, v239, v53, v54
	v_max3_f32 v238, v238, v39, v40
	s_waitcnt lgkmcnt(6)
	v_mfma_f32_32x32x16_bf16 v[80:95], v[200:203], v[128:131], 0
	v_max3_f32 v239, v239, v55, v56
	v_max3_f32 v238, v238, v41, v42
	v_max3_f32 v239, v239, v57, v58
	v_max3_f32 v238, v238, v43, v44
	s_waitcnt lgkmcnt(5)
	v_mfma_f32_32x32x16_bf16 v[64:79], v[204:207], v[132:135], v[64:79]
	v_max3_f32 v239, v239, v59, v60
	v_max3_f32 v238, v238, v45, v46
	v_max3_f32 v239, v239, v61, v62
	s_waitcnt lgkmcnt(4)
	v_mfma_f32_32x32x16_bf16 v[80:95], v[208:211], v[132:135], v[80:95]
	v_max3_f32 v238, v238, v47, v63
	v_max_f32_e32 v238, v238, v239
	v_mov_b32_e32 v239, v238
	s_nop 1
	v_permlane32_swap_b32_e32 v238, v239
	v_max_f32_e32 v238, v238, v239
	v_cmp_lt_f32_e32 vcc, s1, v238
	s_cbranch_vccnz .Lm_rareA
	s_waitcnt lgkmcnt(0)
	ds_read_b64_tr_b16 v[196:197], v178 offset:49920
	ds_read_b64_tr_b16 v[198:199], v178 offset:50432
	ds_read_b64_tr_b16 v[200:201], v178 offset:54016
	ds_read_b64_tr_b16 v[202:203], v178 offset:54528
	ds_read_b64_tr_b16 v[204:205], v178 offset:50944
	ds_read_b64_tr_b16 v[206:207], v178 offset:51456
	ds_read_b64_tr_b16 v[208:209], v178 offset:55040
	ds_read_b64_tr_b16 v[210:211], v178 offset:55552
	v_exp_f32_e32 v32, v32
	v_exp_f32_e32 v48, v48
	v_exp_f32_e32 v33, v33
	v_exp_f32_e32 v49, v49
	v_mfma_f32_32x32x16_bf16 v[64:79], v[212:215], v[136:139], v[64:79]
	v_exp_f32_e32 v34, v34
	v_exp_f32_e32 v50, v50
	v_exp_f32_e32 v35, v35
	v_exp_f32_e32 v51, v51
	v_exp_f32_e32 v36, v36
	v_exp_f32_e32 v52, v52
	v_mfma_f32_32x32x16_bf16 v[80:95], v[216:219], v[136:139], v[80:95]
	v_exp_f32_e32 v37, v37
	v_exp_f32_e32 v53, v53
	v_exp_f32_e32 v38, v38
	v_exp_f32_e32 v54, v54
	v_exp_f32_e32 v39, v39
	v_exp_f32_e32 v55, v55
	v_mfma_f32_32x32x16_bf16 v[64:79], v[188:191], v[140:143], v[64:79]
	v_exp_f32_e32 v40, v40
	v_exp_f32_e32 v56, v56
	v_exp_f32_e32 v41, v41
	v_exp_f32_e32 v57, v57
	v_exp_f32_e32 v42, v42
	v_exp_f32_e32 v58, v58
	v_mfma_f32_32x32x16_bf16 v[80:95], v[224:227], v[140:143], v[80:95]
	v_exp_f32_e32 v43, v43
	v_exp_f32_e32 v59, v59
	v_exp_f32_e32 v44, v44
	v_exp_f32_e32 v60, v60
	v_exp_f32_e32 v45, v45
	v_exp_f32_e32 v61, v61
	v_exp_f32_e32 v46, v46
	v_exp_f32_e32 v62, v62
	v_exp_f32_e32 v47, v47
	v_exp_f32_e32 v63, v63
	s_waitcnt lgkmcnt(7)
	ds_read_b64_tr_b16 v[212:213], v178 offset:51968
	ds_read_b64_tr_b16 v[214:215], v178 offset:52480
	ds_read_b64_tr_b16 v[216:217], v178 offset:56064
	ds_read_b64_tr_b16 v[218:219], v178 offset:56576
	ds_read_b64_tr_b16 v[188:189], v178 offset:52992
	ds_read_b64_tr_b16 v[190:191], v178 offset:53504
	ds_read_b64_tr_b16 v[224:225], v178 offset:57088
	ds_read_b64_tr_b16 v[226:227], v178 offset:57600
	v_add_f32_e32 v238, v52, v36
	v_add_f32_e32 v239, v53, v37
	v_add_f32_e32 v240, v48, v32
	v_add_f32_e32 v241, v49, v33
	v_add_f32_e32 v242, v54, v38
	v_add_f32_e32 v243, v55, v39
	v_add_f32_e32 v244, v50, v34
	v_add_f32_e32 v245, v51, v35
	s_mov_b64 exec, s[6:7]
	v_cvt_pk_bf16_f32 v156, v32, v33
	v_cvt_pk_bf16_f32 v157, v34, v35
	v_cvt_pk_bf16_f32 v158, v36, v37
	v_cvt_pk_bf16_f32 v159, v38, v39
	s_mov_b64 exec, -1
	v_add_f32_e32 v246, v58, v42
	v_add_f32_e32 v247, v59, v43
	v_add_f32_e32 v248, v56, v40
	v_add_f32_e32 v249, v57, v41
	s_waitcnt lgkmcnt(14)
	v_mfma_f32_32x32x16_bf16 v[16:31], v[156:159], v[196:199], v[16:31]
	v_add_f32_e32 v242, v244, v242
	v_add_f32_e32 v243, v245, v243
	v_add_f32_e32 v238, v240, v238
	v_add_f32_e32 v239, v241, v239
	s_mov_b64 exec, s[6:7]
	v_cvt_pk_bf16_f32 v152, v40, v41
	v_cvt_pk_bf16_f32 v153, v42, v43
	v_cvt_pk_bf16_f32 v154, v44, v45
	v_cvt_pk_bf16_f32 v155, v46, v47
	s_mov_b64 exec, -1
	s_waitcnt lgkmcnt(12)
	v_mfma_f32_32x32x16_bf16 v[0:15], v[156:159], v[200:203], v[0:15]
	v_add_f32_e32 v240, v60, v44
	v_add_f32_e32 v241, v61, v45
	v_add_f32_e32 v244, v62, v46
	v_add_f32_e32 v245, v63, v47
	s_waitcnt lgkmcnt(10)
	v_mfma_f32_32x32x16_bf16 v[16:31], v[152:155], v[204:207], v[16:31]
	v_add_f32_e32 v248, v248, v238
	v_add_f32_e32 v249, v249, v239
	v_add_f32_e32 v246, v246, v242
	v_add_f32_e32 v247, v247, v243
	s_mov_b64 exec, s[6:7]
	v_cvt_pk_bf16_f32 v148, v48, v49
	v_cvt_pk_bf16_f32 v149, v50, v51
	v_cvt_pk_bf16_f32 v150, v52, v53
	v_cvt_pk_bf16_f32 v151, v54, v55
	s_mov_b64 exec, -1
	s_waitcnt lgkmcnt(8)
	v_mfma_f32_32x32x16_bf16 v[0:15], v[152:155], v[208:211], v[0:15]
	v_add_f32_e32 v182, v240, v248
	v_add_f32_e32 v183, v241, v249
	v_add_f32_e32 v180, v244, v246
	v_add_f32_e32 v181, v245, v247
	s_waitcnt lgkmcnt(6)
	v_mfma_f32_32x32x16_bf16 v[16:31], v[148:151], v[212:215], v[16:31]
	v_pk_mov_b32 v[184:185], v[182:183], v[180:181] op_sel:[1,0]
	v_mov_b32_e32 v183, v181
	s_mov_b64 exec, s[6:7]
	v_cvt_pk_bf16_f32 v144, v56, v57
	v_cvt_pk_bf16_f32 v145, v58, v59
	v_cvt_pk_bf16_f32 v146, v60, v61
	v_cvt_pk_bf16_f32 v147, v62, v63
	s_mov_b64 exec, -1
	s_waitcnt lgkmcnt(4)
	v_mfma_f32_32x32x16_bf16 v[0:15], v[148:151], v[216:219], v[0:15]
	v_add_f32_e32 v180, v184, v182
	v_add_f32_e32 v181, v185, v183
	s_waitcnt lgkmcnt(2)
	v_mfma_f32_32x32x16_bf16 v[16:31], v[144:147], v[188:191], v[16:31]
	v_add_f32_e32 v181, v180, v181
	v_cndmask_b32_e64 v181, 0, v181, s[6:7]
	v_add_f32_e32 v177, v177, v181
	s_waitcnt lgkmcnt(0)
	v_mfma_f32_32x32x16_bf16 v[0:15], v[144:147], v[224:227], v[0:15]
	v_add_u32_e32 v180, 0, v178
	s_andn2_b64 s[8:9], exec, s[54:55]
	s_branch .Lm_halfB

.Lm_fastB:
	v_add_u32_e32 v251, 0x10100, v178
	ds_read_b128 v[196:199], v179 offset:8320
	ds_read_b128 v[200:203], v179 offset:8832
	ds_read_b128 v[204:207], v179 offset:10400
	ds_read_b128 v[208:211], v179 offset:10912
	ds_read_b128 v[212:215], v179 offset:12480
	ds_read_b128 v[216:219], v179 offset:12992
	ds_read_b128 v[188:191], v179 offset:14560
	ds_read_b128 v[224:227], v179 offset:15072
	v_max_f32_e32 v238, v64, v64
	v_max_f32_e32 v239, v80, v80
	v_max3_f32 v238, v238, v65, v66
	v_max3_f32 v239, v239, v81, v82
	v_max3_f32 v238, v238, v67, v68
	s_waitcnt lgkmcnt(7)
	v_mfma_f32_32x32x16_bf16 v[32:47], v[196:199], v[128:131], 0
	v_max3_f32 v239, v239, v83, v84
	v_max3_f32 v238, v238, v69, v70
	v_max3_f32 v239, v239, v85, v86
	v_max3_f32 v238, v238, v71, v72
	s_waitcnt lgkmcnt(6)
	v_mfma_f32_32x32x16_bf16 v[48:63], v[200:203], v[128:131], 0
	v_max3_f32 v239, v239, v87, v88
	v_max3_f32 v238, v238, v73, v74
	v_max3_f32 v239, v239, v89, v90
	v_max3_f32 v238, v238, v75, v76
	s_waitcnt lgkmcnt(5)
	v_mfma_f32_32x32x16_bf16 v[32:47], v[204:207], v[132:135], v[32:47]
	v_max3_f32 v239, v239, v91, v92
	v_max3_f32 v238, v238, v77, v78
	v_max3_f32 v239, v239, v93, v94
	s_waitcnt lgkmcnt(4)
	v_mfma_f32_32x32x16_bf16 v[48:63], v[208:211], v[132:135], v[48:63]
	v_max3_f32 v238, v238, v79, v95
	v_max_f32_e32 v238, v238, v239
	v_mov_b32_e32 v239, v238
	s_nop 1
	v_permlane32_swap_b32_e32 v238, v239
	v_max_f32_e32 v238, v238, v239
	v_cmp_lt_f32_e32 vcc, s1, v238
	s_cbranch_vccnz .Lm_rareB
	s_waitcnt lgkmcnt(0)
	ds_read_b64_tr_b16 v[196:197], v178 offset:58112
	ds_read_b64_tr_b16 v[198:199], v178 offset:58624
	ds_read_b64_tr_b16 v[200:201], v178 offset:62208
	ds_read_b64_tr_b16 v[202:203], v178 offset:62720
	ds_read_b64_tr_b16 v[204:205], v178 offset:59136
	ds_read_b64_tr_b16 v[206:207], v178 offset:59648
	ds_read_b64_tr_b16 v[208:209], v178 offset:63232
	ds_read_b64_tr_b16 v[210:211], v178 offset:63744
	v_exp_f32_e32 v64, v64
	v_exp_f32_e32 v80, v80
	v_exp_f32_e32 v65, v65
	v_exp_f32_e32 v81, v81
	v_mfma_f32_32x32x16_bf16 v[32:47], v[212:215], v[136:139], v[32:47]
	v_exp_f32_e32 v66, v66
	v_exp_f32_e32 v82, v82
	v_exp_f32_e32 v67, v67
	v_exp_f32_e32 v83, v83
	v_exp_f32_e32 v68, v68
	v_exp_f32_e32 v84, v84
	v_mfma_f32_32x32x16_bf16 v[48:63], v[216:219], v[136:139], v[48:63]
	v_exp_f32_e32 v69, v69
	v_exp_f32_e32 v85, v85
	v_exp_f32_e32 v70, v70
	v_exp_f32_e32 v86, v86
	v_exp_f32_e32 v71, v71
	v_exp_f32_e32 v87, v87
	v_mfma_f32_32x32x16_bf16 v[32:47], v[188:191], v[140:143], v[32:47]
	v_exp_f32_e32 v72, v72
	v_exp_f32_e32 v88, v88
	v_exp_f32_e32 v73, v73
	v_exp_f32_e32 v89, v89
	v_exp_f32_e32 v74, v74
	v_exp_f32_e32 v90, v90
	v_mfma_f32_32x32x16_bf16 v[48:63], v[224:227], v[140:143], v[48:63]
	v_exp_f32_e32 v75, v75
	v_exp_f32_e32 v91, v91
	v_exp_f32_e32 v76, v76
	v_exp_f32_e32 v92, v92
	v_exp_f32_e32 v77, v77
	v_exp_f32_e32 v93, v93
	v_exp_f32_e32 v78, v78
	v_exp_f32_e32 v94, v94
	v_exp_f32_e32 v79, v79
	v_exp_f32_e32 v95, v95
	s_waitcnt lgkmcnt(7)
	ds_read_b64_tr_b16 v[212:213], v178 offset:60160
	ds_read_b64_tr_b16 v[214:215], v178 offset:60672
	ds_read_b64_tr_b16 v[216:217], v178 offset:64256
	ds_read_b64_tr_b16 v[218:219], v178 offset:64768
	ds_read_b64_tr_b16 v[188:189], v178 offset:61184
	ds_read_b64_tr_b16 v[190:191], v178 offset:61696
	ds_read_b64_tr_b16 v[224:225], v178 offset:65280
	ds_read_b64_tr_b16 v[226:227], v251
	v_add_f32_e32 v238, v84, v68
	v_add_f32_e32 v239, v85, v69
	v_add_f32_e32 v240, v80, v64
	v_add_f32_e32 v241, v81, v65
	v_add_f32_e32 v242, v86, v70
	v_add_f32_e32 v243, v87, v71
	v_add_f32_e32 v244, v82, v66
	v_add_f32_e32 v245, v83, v67
	s_mov_b64 exec, s[6:7]
	v_cvt_pk_bf16_f32 v156, v64, v65
	v_cvt_pk_bf16_f32 v157, v66, v67
	v_cvt_pk_bf16_f32 v158, v68, v69
	v_cvt_pk_bf16_f32 v159, v70, v71
	s_mov_b64 exec, -1
	v_add_f32_e32 v246, v90, v74
	v_add_f32_e32 v247, v91, v75
	v_add_f32_e32 v248, v88, v72
	v_add_f32_e32 v249, v89, v73
	s_waitcnt lgkmcnt(14)
	v_mfma_f32_32x32x16_bf16 v[16:31], v[156:159], v[196:199], v[16:31]
	v_add_f32_e32 v242, v244, v242
	v_add_f32_e32 v243, v245, v243
	v_add_f32_e32 v238, v240, v238
	v_add_f32_e32 v239, v241, v239
	s_mov_b64 exec, s[6:7]
	v_cvt_pk_bf16_f32 v152, v72, v73
	v_cvt_pk_bf16_f32 v153, v74, v75
	v_cvt_pk_bf16_f32 v154, v76, v77
	v_cvt_pk_bf16_f32 v155, v78, v79
	s_mov_b64 exec, -1
	s_waitcnt lgkmcnt(12)
	v_mfma_f32_32x32x16_bf16 v[0:15], v[156:159], v[200:203], v[0:15]
	v_add_f32_e32 v240, v92, v76
	v_add_f32_e32 v241, v93, v77
	v_add_f32_e32 v244, v94, v78
	v_add_f32_e32 v245, v95, v79
	s_waitcnt lgkmcnt(10)
	v_mfma_f32_32x32x16_bf16 v[16:31], v[152:155], v[204:207], v[16:31]
	v_add_f32_e32 v248, v248, v238
	v_add_f32_e32 v249, v249, v239
	v_add_f32_e32 v246, v246, v242
	v_add_f32_e32 v247, v247, v243
	s_mov_b64 exec, s[6:7]
	v_cvt_pk_bf16_f32 v148, v80, v81
	v_cvt_pk_bf16_f32 v149, v82, v83
	v_cvt_pk_bf16_f32 v150, v84, v85
	v_cvt_pk_bf16_f32 v151, v86, v87
	s_mov_b64 exec, -1
	s_waitcnt lgkmcnt(8)
	v_mfma_f32_32x32x16_bf16 v[0:15], v[152:155], v[208:211], v[0:15]
	v_add_f32_e32 v184, v240, v248
	v_add_f32_e32 v185, v241, v249
	v_add_f32_e32 v182, v244, v246
	v_add_f32_e32 v183, v245, v247
	s_waitcnt lgkmcnt(6)
	v_mfma_f32_32x32x16_bf16 v[16:31], v[148:151], v[212:215], v[16:31]
	v_pk_mov_b32 v[186:187], v[184:185], v[182:183] op_sel:[1,0]
	v_mov_b32_e32 v185, v183
	s_mov_b64 exec, s[6:7]
	v_cvt_pk_bf16_f32 v144, v88, v89
	v_cvt_pk_bf16_f32 v145, v90, v91
	v_cvt_pk_bf16_f32 v146, v92, v93
	v_cvt_pk_bf16_f32 v147, v94, v95
	s_mov_b64 exec, -1
	s_waitcnt lgkmcnt(4)
	v_mfma_f32_32x32x16_bf16 v[0:15], v[148:151], v[216:219], v[0:15]
	v_add_f32_e32 v182, v186, v184
	v_add_f32_e32 v183, v187, v185
	s_waitcnt lgkmcnt(2)
	v_mfma_f32_32x32x16_bf16 v[16:31], v[144:147], v[188:191], v[16:31]
	v_add_f32_e32 v181, v182, v183
	v_cndmask_b32_e64 v181, 0, v181, s[6:7]
	v_add_f32_e32 v177, v177, v181
	s_waitcnt lgkmcnt(0)
	v_mfma_f32_32x32x16_bf16 v[0:15], v[144:147], v[224:227], v[0:15]
	v_add_u32_e32 v179, 0x4100, v179
	v_add_u32_e32 v178, 0x4000, v178
	s_add_i32 s71, s71, 2
	s_addk_i32 s70, 0x80
	s_branch .LBB0_349
